# SwiGLU epilogue: row statistics of the next row group requested one group ahead (ping-pong registers), counted vmcnt(3) instead of vmcnt(0) after each output store
# baseline (speedup 1.0000x reference)
; DI float bperm(float v, int srclane) { return __int_as_float(__builtin_amdgcn_ds_bpermute(srclane << 2, __float_as_int(v))); }
; DI unsigned pk2(float lo, float hi) { const f32x2 v = {lo, hi}; const hwbf16x2 b = __builtin_convertvector(v, hwbf16x2); return __builtin_bit_cast(unsigned, b); }
; DI float silu_f(float x) { return x * __builtin_amdgcn_rcpf(1.0f + __expf(-x)); }
; DI void row_stats(const float* STAT, int row, int fq, int lane, float& mu, float& rstd) {
;     const f32x4 a = *(const f32x4*)(STAT + (size_t)row * 32 + fq * 8), b = *(const f32x4*)(STAT + (size_t)row * 32 + fq * 8 + 4);
;     float s = (a[0] + a[2]) + (b[0] + b[2]), q = (a[1] + a[3]) + (b[1] + b[3]);
;     s += bperm(s, lane ^ 16); q += bperm(q, lane ^ 16); s += bperm(s, lane ^ 32); q += bperm(q, lane ^ 32);
;     mu = s * (1.0f / 1024.0f); rstd = __builtin_amdgcn_rsqf(fmaxf(q * (1.0f / 1024.0f) - mu * mu, 0.f) + EPS);
; }
;     DI void operator()(const f32x4 (&acc)[2][2][4][2], const pg8::Unit& u, int wr, int wc, int fr, int fq) const {
;     ...
;             for (int n = 0; n < 2; ++n) { c1[bj][n] = *(const f32x4*)(C1 + cc + bj * 128 + n * 4); c2[bj][n] = *(const f32x4*)(C2 + cc + bj * 128 + n * 4); }
; #pragma unroll
;         for (int ai = 0; ai < 2; ++ai)
; #pragma unroll
;             for (int m = 0; m < 4; ++m) { const int row = row0 + ai * 128 + m * 16; float mu, rstd; row_stats(STAT, row, fq, lane, mu, rstd);
;                 const f32x4 g0 = (acc[ai][0][m][0] - c1[0][0] * mu) * rstd + c2[0][0], g1 = (acc[ai][0][m][1] - c1[0][1] * mu) * rstd + c2[0][1];
;                 const f32x4 u0 = (acc[ai][1][m][0] - c1[1][0] * mu) * rstd + c2[1][0], u1 = (acc[ai][1][m][1] - c1[1][1] * mu) * rstd + c2[1][1];
;                 u32x4 w; w.x = pk2(silu_f(g0[0]) * u0[0], silu_f(g0[1]) * u0[1]); w.y = pk2(silu_f(g0[2]) * u0[2], silu_f(g0[3]) * u0[3]);
;                 w.z = pk2(silu_f(g1[0]) * u1[0], silu_f(g1[1]) * u1[1]); w.w = pk2(silu_f(g1[2]) * u1[2], silu_f(g1[3]) * u1[3]);
;                 *(u32x4*)(HID + (size_t)row * DFF + col0) = w; }
.LBB0_1896:
	v_mov_b32_e32 v173, v178
	v_mov_b32_e32 v177, v179
	s_lshl_b32 s2, s34, 8
	s_add_i32 s2, s2, s58
	v_add_u32_e32 v172, s2, v173
	s_lshl_b32 s2, s15, 8
	v_lshlrev_b32_e32 v173, 2, v173
	v_lshlrev_b32_e32 v174, 3, v177
	s_or_b32 s2, s2, s82
	v_lshl_add_u32 v173, v177, 6, v173
	v_add_u32_e32 v34, s2, v174
	s_lshl_b32 s2, s15, 7
	v_xor_b32_e32 v183, 64, v173
	v_xor_b32_e32 v182, 0x80, v173
	v_ashrrev_i32_e32 v173, 31, v172
	v_ashrrev_i32_e32 v35, 31, v34
	s_or_b32 s2, s2, s82
	v_ashrrev_i32_e32 v175, 31, v174
	v_lshlrev_b64 v[184:185], 7, v[172:173]
	v_lshlrev_b64 v[34:35], 2, v[34:35]
	v_add_u32_e32 v176, s2, v174
	v_lshl_add_u64 v[184:185], s[22:23], 0, v[184:185]
	v_lshlrev_b64 v[174:175], 2, v[174:175]
	v_lshl_add_u64 v[36:37], s[24:25], 0, v[34:35]
	v_lshl_add_u64 v[50:51], s[26:27], 0, v[34:35]
	v_lshl_add_u64 v[196:197], v[184:185], 0, v[174:175]
	global_load_dwordx4 v[46:49], v[36:37], off offset:16
	global_load_dwordx4 v[62:65], v[36:37], off
	global_load_dwordx4 v[42:45], v[50:51], off offset:16
	global_load_dwordx4 v[58:61], v[50:51], off
	global_load_dwordx4 v[38:41], v[36:37], off offset:528
	global_load_dwordx4 v[54:57], v[36:37], off offset:512
	s_nop 0
	global_load_dwordx4 v[34:37], v[50:51], off offset:528
	s_nop 0
	global_load_dwordx4 v[50:53], v[50:51], off offset:512
	s_nop 0
	global_load_dwordx4 v[184:187], v[196:197], off offset:16
	global_load_dwordx4 v[220:223], v[196:197], off
	v_add_u32_e32 v250, 0x10, v172
	v_ashrrev_i32_e32 v251, 31, v250
	v_lshlrev_b64 v[250:251], 7, v[250:251]
	v_lshl_add_u64 v[250:251], s[22:23], 0, v[250:251]
	v_lshl_add_u64 v[250:251], v[250:251], 0, v[174:175]
	global_load_dwordx4 v[224:227], v[250:251], off offset:16
	global_load_dwordx4 v[228:231], v[250:251], off
	s_mov_b32 s34, 0x3a800000
	v_ashrrev_i32_e32 v177, 31, v176
	s_movk_i32 s15, 0x1600
	s_andn2_b64 vcc, exec, s[16:17]
	v_readlane_b32 s61, v254, 55
	s_waitcnt vmcnt(0)
	v_xor_b32_e32 v49, 0x80000000, v49
	v_xor_b32_e32 v48, 0x80000000, v48
	v_xor_b32_e32 v41, 0x80000000, v41
	v_xor_b32_e32 v40, 0x80000000, v40
	v_xor_b32_e32 v57, 0x80000000, v57
	v_pk_add_f32 v[184:185], v[184:185], v[186:187]
	v_pk_add_f32 v[196:197], v[220:221], v[222:223]
	v_xor_b32_e32 v56, 0x80000000, v56
	v_pk_add_f32 v[184:185], v[196:197], v[184:185]
	ds_bpermute_b32 v186, v183, v184
	ds_bpermute_b32 v187, v183, v185
	s_waitcnt lgkmcnt(0)
	v_pk_add_f32 v[184:185], v[184:185], v[186:187]
	ds_bpermute_b32 v186, v182, v184
	ds_bpermute_b32 v187, v182, v185
	s_waitcnt lgkmcnt(0)
	v_pk_add_f32 v[184:185], v[184:185], v[186:187]
	s_nop 0
	v_pk_mul_f32 v[184:185], v[184:185], s[34:35] op_sel_hi:[1,0]
	s_nop 0
	v_fma_f32 v173, -v184, v184, v185
	v_max_f32_e32 v173, 0, v173
	v_add_f32_e32 v173, 0x3727c5ac, v173
	v_rsq_f32_e32 v186, v173
	v_pk_fma_f32 v[196:197], v[62:63], v[184:185], v[158:159] op_sel_hi:[1,0,1] neg_lo:[1,0,0] neg_hi:[1,0,0]
	v_xor_b32_e32 v159, 0x80000000, v65
	v_xor_b32_e32 v158, 0x80000000, v64
	v_pk_fma_f32 v[64:65], v[158:159], v[184:185], v[160:161] op_sel_hi:[1,0,1]
	v_pk_fma_f32 v[160:161], v[196:197], v[186:187], v[58:59] op_sel_hi:[1,0,1]
	v_pk_fma_f32 v[146:147], v[38:39], v[184:185], v[146:147] op_sel_hi:[1,0,1] neg_lo:[1,0,0] neg_hi:[1,0,0]
	v_pk_fma_f32 v[148:149], v[40:41], v[184:185], v[148:149] op_sel_hi:[1,0,1]
	v_pk_fma_f32 v[154:155], v[46:47], v[184:185], v[154:155] op_sel_hi:[1,0,1] neg_lo:[1,0,0] neg_hi:[1,0,0]
	v_pk_fma_f32 v[156:157], v[48:49], v[184:185], v[156:157] op_sel_hi:[1,0,1]
	v_pk_fma_f32 v[150:151], v[54:55], v[184:185], v[150:151] op_sel_hi:[1,0,1] neg_lo:[1,0,0] neg_hi:[1,0,0]
	v_pk_fma_f32 v[152:153], v[56:57], v[184:185], v[152:153] op_sel_hi:[1,0,1]
	v_pk_fma_f32 v[184:185], v[148:149], v[186:187], v[36:37] op_sel_hi:[1,0,1]
	v_pk_fma_f32 v[148:149], v[146:147], v[186:187], v[34:35] op_sel_hi:[1,0,1]
	v_mul_f32_e32 v146, 0xbfb8aa3b, v160
	v_mul_f32_e32 v147, 0xbfb8aa3b, v161
	v_exp_f32_e32 v146, v146
	v_exp_f32_e32 v147, v147
	v_pk_fma_f32 v[150:151], v[150:151], v[186:187], v[50:51] op_sel_hi:[1,0,1]
	v_pk_fma_f32 v[64:65], v[64:65], v[186:187], v[60:61] op_sel_hi:[1,0,1]
	v_add_f32_e32 v146, 1.0, v146
	v_add_f32_e32 v147, 1.0, v147
	v_rcp_f32_e32 v146, v146
	v_rcp_f32_e32 v147, v147
	v_pk_fma_f32 v[152:153], v[152:153], v[186:187], v[52:53] op_sel_hi:[1,0,1]
	v_pk_fma_f32 v[154:155], v[154:155], v[186:187], v[42:43] op_sel_hi:[1,0,1]
	v_pk_fma_f32 v[156:157], v[156:157], v[186:187], v[44:45] op_sel_hi:[1,0,1]
	v_pk_mul_f32 v[146:147], v[160:161], v[146:147]
	s_nop 0
	v_pk_mul_f32 v[146:147], v[150:151], v[146:147]
	s_nop 0
	v_cvt_pk_bf16_f32 v146, v146, v147
	v_mul_f32_e32 v147, 0xbfb8aa3b, v64
	v_exp_f32_e32 v147, v147
	s_nop 0
	v_add_f32_e32 v147, 1.0, v147
	v_rcp_f32_e32 v150, v147
	v_mul_f32_e32 v147, 0xbfb8aa3b, v65
	v_exp_f32_e32 v147, v147
	s_nop 0
	v_add_f32_e32 v147, 1.0, v147
	v_rcp_f32_e32 v151, v147
	s_nop 0
	v_pk_mul_f32 v[64:65], v[64:65], v[150:151]
	s_nop 0
	v_pk_mul_f32 v[64:65], v[152:153], v[64:65]
	v_mov_b64_e32 v[150:151], s[20:21]
	v_cvt_pk_bf16_f32 v147, v64, v65
	v_mul_f32_e32 v64, 0xbfb8aa3b, v154
	v_mul_f32_e32 v65, 0xbfb8aa3b, v155
	v_exp_f32_e32 v64, v64
	v_exp_f32_e32 v65, v65
	v_lshlrev_b64 v[152:153], 1, v[176:177]
	v_add_f32_e32 v64, 1.0, v64
	v_add_f32_e32 v65, 1.0, v65
	v_rcp_f32_e32 v64, v64
	v_rcp_f32_e32 v65, v65
	s_nop 0
	v_pk_mul_f32 v[64:65], v[154:155], v[64:65]
	s_nop 0
	v_pk_mul_f32 v[64:65], v[148:149], v[64:65]
	s_nop 0
	v_cvt_pk_bf16_f32 v148, v64, v65
	v_mul_f32_e32 v64, 0xbfb8aa3b, v156
	v_mul_f32_e32 v65, 0xbfb8aa3b, v157
	v_exp_f32_e32 v64, v64
	v_exp_f32_e32 v65, v65
	v_add_f32_e32 v64, 1.0, v64
	v_add_f32_e32 v65, 1.0, v65
	v_rcp_f32_e32 v64, v64
	v_rcp_f32_e32 v65, v65
	s_nop 0
	v_pk_mul_f32 v[64:65], v[156:157], v[64:65]
	s_nop 0
	v_pk_mul_f32 v[64:65], v[184:185], v[64:65]
	s_nop 0
	v_cvt_pk_bf16_f32 v149, v64, v65
	v_mad_i64_i32 v[64:65], s[2:3], v172, s15, v[150:151]
	v_lshl_add_u64 v[64:65], v[64:65], 0, v[152:153]
	global_store_dwordx4 v[64:65], v[146:149], off
	v_add_u32_e32 v64, 16, v172
	v_ashrrev_i32_e32 v65, 31, v64
	v_lshlrev_b64 v[146:147], 7, v[64:65]
	v_lshl_add_u64 v[146:147], s[22:23], 0, v[146:147]
	v_lshl_add_u64 v[154:155], v[146:147], 0, v[174:175]
	v_add_u32_e32 v250, 0x20, v172
	v_ashrrev_i32_e32 v251, 31, v250
	v_lshlrev_b64 v[250:251], 7, v[250:251]
	v_lshl_add_u64 v[250:251], s[22:23], 0, v[250:251]
	v_lshl_add_u64 v[250:251], v[250:251], 0, v[174:175]
	global_load_dwordx4 v[232:235], v[250:251], off offset:16
	global_load_dwordx4 v[236:239], v[250:251], off
	s_nop 0
	s_nop 0
	s_waitcnt vmcnt(3)
; DI float bperm(float v, int srclane) { return __int_as_float(__builtin_amdgcn_ds_bpermute(srclane << 2, __float_as_int(v))); }
; DI unsigned pk2(float lo, float hi) { const f32x2 v = {lo, hi}; const hwbf16x2 b = __builtin_convertvector(v, hwbf16x2); return __builtin_bit_cast(unsigned, b); }
; DI float silu_f(float x) { return x * __builtin_amdgcn_rcpf(1.0f + __expf(-x)); }
; DI void row_stats(const float* STAT, int row, int fq, int lane, float& mu, float& rstd) {
;     const f32x4 a = *(const f32x4*)(STAT + (size_t)row * 32 + fq * 8), b = *(const f32x4*)(STAT + (size_t)row * 32 + fq * 8 + 4);
;     float s = (a[0] + a[2]) + (b[0] + b[2]), q = (a[1] + a[3]) + (b[1] + b[3]);
;     s += bperm(s, lane ^ 16); q += bperm(q, lane ^ 16); s += bperm(s, lane ^ 32); q += bperm(q, lane ^ 32);
;     mu = s * (1.0f / 1024.0f); rstd = __builtin_amdgcn_rsqf(fmaxf(q * (1.0f / 1024.0f) - mu * mu, 0.f) + EPS);
; }
;     DI void operator()(const f32x4 (&acc)[2][2][4][2], const pg8::Unit& u, int wr, int wc, int fr, int fq) const {
;     ...
;             for (int m = 0; m < 4; ++m) { const int row = row0 + ai * 128 + m * 16; float mu, rstd; row_stats(STAT, row, fq, lane, mu, rstd);
;                 const f32x4 g0 = (acc[ai][0][m][0] - c1[0][0] * mu) * rstd + c2[0][0], g1 = (acc[ai][0][m][1] - c1[0][1] * mu) * rstd + c2[0][1];
;                 const f32x4 u0 = (acc[ai][1][m][0] - c1[1][0] * mu) * rstd + c2[1][0], u1 = (acc[ai][1][m][1] - c1[1][1] * mu) * rstd + c2[1][1];
;                 u32x4 w; w.x = pk2(silu_f(g0[0]) * u0[0], silu_f(g0[1]) * u0[1]); w.y = pk2(silu_f(g0[2]) * u0[2], silu_f(g0[3]) * u0[3]);
;                 w.z = pk2(silu_f(g1[0]) * u1[0], silu_f(g1[1]) * u1[1]); w.w = pk2(silu_f(g1[2]) * u1[2], silu_f(g1[3]) * u1[3]);
;                 *(u32x4*)(HID + (size_t)row * DFF + col0) = w; }
	v_mov_b32_e32 v146, v224
	v_mov_b32_e32 v147, v225
	v_mov_b32_e32 v148, v226
	v_mov_b32_e32 v149, v227
	v_mov_b32_e32 v154, v228
	v_mov_b32_e32 v155, v229
	v_mov_b32_e32 v156, v230
	v_mov_b32_e32 v157, v231
	v_pk_add_f32 v[146:147], v[146:147], v[148:149]
	s_nop 0
	v_pk_add_f32 v[154:155], v[154:155], v[156:157]
	s_nop 0
	v_pk_add_f32 v[146:147], v[154:155], v[146:147]
	ds_bpermute_b32 v148, v183, v146
	ds_bpermute_b32 v149, v183, v147
	s_waitcnt lgkmcnt(0)
	v_pk_add_f32 v[146:147], v[146:147], v[148:149]
	ds_bpermute_b32 v148, v182, v146
	ds_bpermute_b32 v149, v182, v147
	s_waitcnt lgkmcnt(0)
	v_pk_add_f32 v[146:147], v[146:147], v[148:149]
	s_nop 0
	v_pk_mul_f32 v[146:147], v[146:147], s[34:35] op_sel_hi:[1,0]
	s_nop 0
	v_fma_f32 v65, -v146, v146, v147
	v_max_f32_e32 v65, 0, v65
	v_add_f32_e32 v65, 0x3727c5ac, v65
	v_rsq_f32_e32 v148, v65
	v_pk_fma_f32 v[142:143], v[62:63], v[146:147], v[142:143] op_sel_hi:[1,0,1] neg_lo:[1,0,0] neg_hi:[1,0,0]
	v_pk_fma_f32 v[130:131], v[38:39], v[146:147], v[130:131] op_sel_hi:[1,0,1] neg_lo:[1,0,0] neg_hi:[1,0,0]
	v_pk_fma_f32 v[132:133], v[40:41], v[146:147], v[132:133] op_sel_hi:[1,0,1]
	v_pk_fma_f32 v[142:143], v[142:143], v[148:149], v[58:59] op_sel_hi:[1,0,1]
	v_pk_fma_f32 v[144:145], v[158:159], v[146:147], v[144:145] op_sel_hi:[1,0,1]
	v_mul_f32_e32 v65, 0xbfb8aa3b, v142
	v_exp_f32_e32 v65, v65
	v_pk_fma_f32 v[138:139], v[46:47], v[146:147], v[138:139] op_sel_hi:[1,0,1] neg_lo:[1,0,0] neg_hi:[1,0,0]
	v_pk_fma_f32 v[140:141], v[48:49], v[146:147], v[140:141] op_sel_hi:[1,0,1]
	v_pk_fma_f32 v[134:135], v[54:55], v[146:147], v[134:135] op_sel_hi:[1,0,1] neg_lo:[1,0,0] neg_hi:[1,0,0]
	v_add_f32_e32 v65, 1.0, v65
	v_pk_fma_f32 v[136:137], v[56:57], v[146:147], v[136:137] op_sel_hi:[1,0,1]
	v_pk_fma_f32 v[146:147], v[132:133], v[148:149], v[36:37] op_sel_hi:[1,0,1]
	v_pk_fma_f32 v[132:133], v[130:131], v[148:149], v[34:35] op_sel_hi:[1,0,1]
	v_rcp_f32_e32 v130, v65
	v_mul_f32_e32 v65, 0xbfb8aa3b, v143
	v_exp_f32_e32 v65, v65
	v_pk_fma_f32 v[144:145], v[144:145], v[148:149], v[60:61] op_sel_hi:[1,0,1]
	v_pk_fma_f32 v[134:135], v[134:135], v[148:149], v[50:51] op_sel_hi:[1,0,1]
	v_pk_fma_f32 v[138:139], v[138:139], v[148:149], v[42:43] op_sel_hi:[1,0,1]
	v_add_f32_e32 v65, 1.0, v65
	v_rcp_f32_e32 v131, v65
	v_mul_f32_e32 v65, 0xbfb8aa3b, v144
	v_exp_f32_e32 v65, v65
	v_pk_fma_f32 v[136:137], v[136:137], v[148:149], v[52:53] op_sel_hi:[1,0,1]
	v_pk_mul_f32 v[130:131], v[142:143], v[130:131]
	v_pk_fma_f32 v[140:141], v[140:141], v[148:149], v[44:45] op_sel_hi:[1,0,1]
	v_add_f32_e32 v65, 1.0, v65
	v_pk_mul_f32 v[130:131], v[134:135], v[130:131]
	v_rcp_f32_e32 v134, v65
	v_mul_f32_e32 v65, 0xbfb8aa3b, v145
	v_exp_f32_e32 v65, v65
	v_cvt_pk_bf16_f32 v130, v130, v131
	v_add_f32_e32 v65, 1.0, v65
	v_rcp_f32_e32 v135, v65
	v_mul_f32_e32 v65, 0xbfb8aa3b, v138
	v_exp_f32_e32 v65, v65
	v_pk_mul_f32 v[134:135], v[144:145], v[134:135]
	s_nop 0
	v_pk_mul_f32 v[134:135], v[136:137], v[134:135]
	v_add_f32_e32 v65, 1.0, v65
	v_cvt_pk_bf16_f32 v131, v134, v135
	v_rcp_f32_e32 v134, v65
	v_mul_f32_e32 v65, 0xbfb8aa3b, v139
	v_exp_f32_e32 v65, v65
	s_nop 0
	v_add_f32_e32 v65, 1.0, v65
	v_rcp_f32_e32 v135, v65
	v_mul_f32_e32 v65, 0xbfb8aa3b, v140
	v_exp_f32_e32 v65, v65
	v_pk_mul_f32 v[134:135], v[138:139], v[134:135]
	s_nop 0
	v_pk_mul_f32 v[132:133], v[132:133], v[134:135]
	v_add_f32_e32 v65, 1.0, v65
	v_rcp_f32_e32 v134, v65
	v_mul_f32_e32 v65, 0xbfb8aa3b, v141
	v_exp_f32_e32 v65, v65
	v_cvt_pk_bf16_f32 v132, v132, v133
	v_add_f32_e32 v65, 1.0, v65
	v_rcp_f32_e32 v135, v65
	v_mad_i64_i32 v[64:65], s[2:3], v64, s15, v[150:151]
	v_lshl_add_u64 v[64:65], v[64:65], 0, v[152:153]
	v_pk_mul_f32 v[134:135], v[140:141], v[134:135]
	s_nop 0
	v_pk_mul_f32 v[134:135], v[146:147], v[134:135]
	s_nop 0
	v_cvt_pk_bf16_f32 v133, v134, v135
	global_store_dwordx4 v[64:65], v[130:133], off
	v_add_u32_e32 v64, 32, v172
	v_ashrrev_i32_e32 v65, 31, v64
	v_lshlrev_b64 v[130:131], 7, v[64:65]
	v_lshl_add_u64 v[130:131], s[22:23], 0, v[130:131]
	v_lshl_add_u64 v[134:135], v[130:131], 0, v[174:175]
	v_add_u32_e32 v250, 0x30, v172
	v_ashrrev_i32_e32 v251, 31, v250
	v_lshlrev_b64 v[250:251], 7, v[250:251]
	v_lshl_add_u64 v[250:251], s[22:23], 0, v[250:251]
	v_lshl_add_u64 v[250:251], v[250:251], 0, v[174:175]
	global_load_dwordx4 v[224:227], v[250:251], off offset:16
	global_load_dwordx4 v[228:231], v[250:251], off
	s_nop 0
	s_nop 0
	s_waitcnt vmcnt(3)
	v_mov_b32_e32 v130, v232
	v_mov_b32_e32 v131, v233
	v_mov_b32_e32 v132, v234
	v_mov_b32_e32 v133, v235
	v_mov_b32_e32 v134, v236
	v_mov_b32_e32 v135, v237
	v_mov_b32_e32 v136, v238
	v_mov_b32_e32 v137, v239
	v_pk_add_f32 v[130:131], v[130:131], v[132:133]
	s_nop 0
	v_pk_add_f32 v[134:135], v[134:135], v[136:137]
	s_nop 0
	v_pk_add_f32 v[130:131], v[134:135], v[130:131]
	ds_bpermute_b32 v132, v183, v130
	ds_bpermute_b32 v133, v183, v131
	s_waitcnt lgkmcnt(0)
	v_pk_add_f32 v[130:131], v[130:131], v[132:133]
	ds_bpermute_b32 v132, v182, v130
	ds_bpermute_b32 v133, v182, v131
	s_waitcnt lgkmcnt(0)
; DI float bperm(float v, int srclane) { return __int_as_float(__builtin_amdgcn_ds_bpermute(srclane << 2, __float_as_int(v))); }
; DI unsigned pk2(float lo, float hi) { const f32x2 v = {lo, hi}; const hwbf16x2 b = __builtin_convertvector(v, hwbf16x2); return __builtin_bit_cast(unsigned, b); }
; DI float silu_f(float x) { return x * __builtin_amdgcn_rcpf(1.0f + __expf(-x)); }
; DI void row_stats(const float* STAT, int row, int fq, int lane, float& mu, float& rstd) {
;     const f32x4 a = *(const f32x4*)(STAT + (size_t)row * 32 + fq * 8), b = *(const f32x4*)(STAT + (size_t)row * 32 + fq * 8 + 4);
;     float s = (a[0] + a[2]) + (b[0] + b[2]), q = (a[1] + a[3]) + (b[1] + b[3]);
;     s += bperm(s, lane ^ 16); q += bperm(q, lane ^ 16); s += bperm(s, lane ^ 32); q += bperm(q, lane ^ 32);
;     mu = s * (1.0f / 1024.0f); rstd = __builtin_amdgcn_rsqf(fmaxf(q * (1.0f / 1024.0f) - mu * mu, 0.f) + EPS);
; }
;     DI void operator()(const f32x4 (&acc)[2][2][4][2], const pg8::Unit& u, int wr, int wc, int fr, int fq) const {
;     ...
;             for (int m = 0; m < 4; ++m) { const int row = row0 + ai * 128 + m * 16; float mu, rstd; row_stats(STAT, row, fq, lane, mu, rstd);
;                 const f32x4 g0 = (acc[ai][0][m][0] - c1[0][0] * mu) * rstd + c2[0][0], g1 = (acc[ai][0][m][1] - c1[0][1] * mu) * rstd + c2[0][1];
;                 const f32x4 u0 = (acc[ai][1][m][0] - c1[1][0] * mu) * rstd + c2[1][0], u1 = (acc[ai][1][m][1] - c1[1][1] * mu) * rstd + c2[1][1];
;                 u32x4 w; w.x = pk2(silu_f(g0[0]) * u0[0], silu_f(g0[1]) * u0[1]); w.y = pk2(silu_f(g0[2]) * u0[2], silu_f(g0[3]) * u0[3]);
;                 w.z = pk2(silu_f(g1[0]) * u1[0], silu_f(g1[1]) * u1[1]); w.w = pk2(silu_f(g1[2]) * u1[2], silu_f(g1[3]) * u1[3]);
;                 *(u32x4*)(HID + (size_t)row * DFF + col0) = w; }
	v_pk_add_f32 v[130:131], v[130:131], v[132:133]
	s_nop 0
	v_pk_mul_f32 v[130:131], v[130:131], s[34:35] op_sel_hi:[1,0]
	s_nop 0
	v_fma_f32 v65, -v130, v130, v131
	v_max_f32_e32 v65, 0, v65
	v_add_f32_e32 v65, 0x3727c5ac, v65
	v_rsq_f32_e32 v132, v65
	v_pk_fma_f32 v[126:127], v[62:63], v[130:131], v[126:127] op_sel_hi:[1,0,1] neg_lo:[1,0,0] neg_hi:[1,0,0]
	v_pk_fma_f32 v[114:115], v[38:39], v[130:131], v[114:115] op_sel_hi:[1,0,1] neg_lo:[1,0,0] neg_hi:[1,0,0]
	v_pk_fma_f32 v[116:117], v[40:41], v[130:131], v[116:117] op_sel_hi:[1,0,1]
	v_pk_fma_f32 v[126:127], v[126:127], v[132:133], v[58:59] op_sel_hi:[1,0,1]
	v_pk_fma_f32 v[128:129], v[158:159], v[130:131], v[128:129] op_sel_hi:[1,0,1]
	v_mul_f32_e32 v65, 0xbfb8aa3b, v126
	v_exp_f32_e32 v65, v65
	v_pk_fma_f32 v[122:123], v[46:47], v[130:131], v[122:123] op_sel_hi:[1,0,1] neg_lo:[1,0,0] neg_hi:[1,0,0]
	v_pk_fma_f32 v[124:125], v[48:49], v[130:131], v[124:125] op_sel_hi:[1,0,1]
	v_pk_fma_f32 v[118:119], v[54:55], v[130:131], v[118:119] op_sel_hi:[1,0,1] neg_lo:[1,0,0] neg_hi:[1,0,0]
	v_add_f32_e32 v65, 1.0, v65
	v_pk_fma_f32 v[120:121], v[56:57], v[130:131], v[120:121] op_sel_hi:[1,0,1]
	v_pk_fma_f32 v[130:131], v[116:117], v[132:133], v[36:37] op_sel_hi:[1,0,1]
	v_pk_fma_f32 v[116:117], v[114:115], v[132:133], v[34:35] op_sel_hi:[1,0,1]
	v_rcp_f32_e32 v114, v65
	v_mul_f32_e32 v65, 0xbfb8aa3b, v127
	v_exp_f32_e32 v65, v65
	v_pk_fma_f32 v[128:129], v[128:129], v[132:133], v[60:61] op_sel_hi:[1,0,1]
	v_pk_fma_f32 v[118:119], v[118:119], v[132:133], v[50:51] op_sel_hi:[1,0,1]
	v_pk_fma_f32 v[122:123], v[122:123], v[132:133], v[42:43] op_sel_hi:[1,0,1]
	v_add_f32_e32 v65, 1.0, v65
	v_rcp_f32_e32 v115, v65
	v_mul_f32_e32 v65, 0xbfb8aa3b, v128
	v_exp_f32_e32 v65, v65
	v_pk_fma_f32 v[120:121], v[120:121], v[132:133], v[52:53] op_sel_hi:[1,0,1]
	v_pk_mul_f32 v[114:115], v[126:127], v[114:115]
	v_pk_fma_f32 v[124:125], v[124:125], v[132:133], v[44:45] op_sel_hi:[1,0,1]
	v_add_f32_e32 v65, 1.0, v65
	v_pk_mul_f32 v[114:115], v[118:119], v[114:115]
	v_rcp_f32_e32 v118, v65
	v_mul_f32_e32 v65, 0xbfb8aa3b, v129
	v_exp_f32_e32 v65, v65
	v_cvt_pk_bf16_f32 v114, v114, v115
	v_add_f32_e32 v65, 1.0, v65
	v_rcp_f32_e32 v119, v65
	v_mul_f32_e32 v65, 0xbfb8aa3b, v122
	v_exp_f32_e32 v65, v65
	v_pk_mul_f32 v[118:119], v[128:129], v[118:119]
	s_nop 0
	v_pk_mul_f32 v[118:119], v[120:121], v[118:119]
	v_add_f32_e32 v65, 1.0, v65
	v_cvt_pk_bf16_f32 v115, v118, v119
	v_rcp_f32_e32 v118, v65
	v_mul_f32_e32 v65, 0xbfb8aa3b, v123
	v_exp_f32_e32 v65, v65
	s_nop 0
	v_add_f32_e32 v65, 1.0, v65
	v_rcp_f32_e32 v119, v65
	v_mul_f32_e32 v65, 0xbfb8aa3b, v124
	v_exp_f32_e32 v65, v65
	v_pk_mul_f32 v[118:119], v[122:123], v[118:119]
	s_nop 0
	v_pk_mul_f32 v[116:117], v[116:117], v[118:119]
	v_add_f32_e32 v65, 1.0, v65
	v_rcp_f32_e32 v118, v65
	v_mul_f32_e32 v65, 0xbfb8aa3b, v125
	v_exp_f32_e32 v65, v65
	v_cvt_pk_bf16_f32 v116, v116, v117
	v_add_f32_e32 v65, 1.0, v65
	v_rcp_f32_e32 v119, v65
	v_mad_i64_i32 v[64:65], s[2:3], v64, s15, v[150:151]
	v_lshl_add_u64 v[64:65], v[64:65], 0, v[152:153]
	v_pk_mul_f32 v[118:119], v[124:125], v[118:119]
	s_nop 0
	v_pk_mul_f32 v[118:119], v[130:131], v[118:119]
	s_nop 0
	v_cvt_pk_bf16_f32 v117, v118, v119
	global_store_dwordx4 v[64:65], v[114:117], off
	v_add_u32_e32 v64, 48, v172
	v_ashrrev_i32_e32 v65, 31, v64
	v_lshlrev_b64 v[114:115], 7, v[64:65]
	v_lshl_add_u64 v[114:115], s[22:23], 0, v[114:115]
	v_lshl_add_u64 v[118:119], v[114:115], 0, v[174:175]
	v_add_u32_e32 v250, 0x80, v172
	v_ashrrev_i32_e32 v251, 31, v250
	v_lshlrev_b64 v[250:251], 7, v[250:251]
	v_lshl_add_u64 v[250:251], s[22:23], 0, v[250:251]
	v_lshl_add_u64 v[250:251], v[250:251], 0, v[174:175]
	global_load_dwordx4 v[232:235], v[250:251], off offset:16
	global_load_dwordx4 v[236:239], v[250:251], off
	s_nop 0
	s_nop 0
	s_waitcnt vmcnt(3)
	v_mov_b32_e32 v114, v224
	v_mov_b32_e32 v115, v225
	v_mov_b32_e32 v116, v226
	v_mov_b32_e32 v117, v227
	v_mov_b32_e32 v118, v228
	v_mov_b32_e32 v119, v229
	v_mov_b32_e32 v120, v230
	v_mov_b32_e32 v121, v231
	v_pk_add_f32 v[114:115], v[114:115], v[116:117]
	s_nop 0
	v_pk_add_f32 v[118:119], v[118:119], v[120:121]
	s_nop 0
	v_pk_add_f32 v[114:115], v[118:119], v[114:115]
	ds_bpermute_b32 v116, v183, v114
	ds_bpermute_b32 v117, v183, v115
	s_waitcnt lgkmcnt(0)
	v_pk_add_f32 v[114:115], v[114:115], v[116:117]
	ds_bpermute_b32 v116, v182, v114
	ds_bpermute_b32 v117, v182, v115
	s_waitcnt lgkmcnt(0)
; DI float bperm(float v, int srclane) { return __int_as_float(__builtin_amdgcn_ds_bpermute(srclane << 2, __float_as_int(v))); }
; DI unsigned pk2(float lo, float hi) { const f32x2 v = {lo, hi}; const hwbf16x2 b = __builtin_convertvector(v, hwbf16x2); return __builtin_bit_cast(unsigned, b); }
; DI float silu_f(float x) { return x * __builtin_amdgcn_rcpf(1.0f + __expf(-x)); }
; DI void row_stats(const float* STAT, int row, int fq, int lane, float& mu, float& rstd) {
;     const f32x4 a = *(const f32x4*)(STAT + (size_t)row * 32 + fq * 8), b = *(const f32x4*)(STAT + (size_t)row * 32 + fq * 8 + 4);
;     float s = (a[0] + a[2]) + (b[0] + b[2]), q = (a[1] + a[3]) + (b[1] + b[3]);
;     s += bperm(s, lane ^ 16); q += bperm(q, lane ^ 16); s += bperm(s, lane ^ 32); q += bperm(q, lane ^ 32);
;     mu = s * (1.0f / 1024.0f); rstd = __builtin_amdgcn_rsqf(fmaxf(q * (1.0f / 1024.0f) - mu * mu, 0.f) + EPS);
; }
;     DI void operator()(const f32x4 (&acc)[2][2][4][2], const pg8::Unit& u, int wr, int wc, int fr, int fq) const {
;     ...
;             for (int m = 0; m < 4; ++m) { const int row = row0 + ai * 128 + m * 16; float mu, rstd; row_stats(STAT, row, fq, lane, mu, rstd);
;                 const f32x4 g0 = (acc[ai][0][m][0] - c1[0][0] * mu) * rstd + c2[0][0], g1 = (acc[ai][0][m][1] - c1[0][1] * mu) * rstd + c2[0][1];
;                 const f32x4 u0 = (acc[ai][1][m][0] - c1[1][0] * mu) * rstd + c2[1][0], u1 = (acc[ai][1][m][1] - c1[1][1] * mu) * rstd + c2[1][1];
;                 u32x4 w; w.x = pk2(silu_f(g0[0]) * u0[0], silu_f(g0[1]) * u0[1]); w.y = pk2(silu_f(g0[2]) * u0[2], silu_f(g0[3]) * u0[3]);
;                 w.z = pk2(silu_f(g1[0]) * u1[0], silu_f(g1[1]) * u1[1]); w.w = pk2(silu_f(g1[2]) * u1[2], silu_f(g1[3]) * u1[3]);
;                 *(u32x4*)(HID + (size_t)row * DFF + col0) = w; }
	v_pk_add_f32 v[114:115], v[114:115], v[116:117]
	s_nop 0
	v_pk_mul_f32 v[114:115], v[114:115], s[34:35] op_sel_hi:[1,0]
	s_nop 0
	v_fma_f32 v65, -v114, v114, v115
	v_max_f32_e32 v65, 0, v65
	v_add_f32_e32 v65, 0x3727c5ac, v65
	v_rsq_f32_e32 v116, v65
	v_pk_fma_f32 v[110:111], v[62:63], v[114:115], v[110:111] op_sel_hi:[1,0,1] neg_lo:[1,0,0] neg_hi:[1,0,0]
	v_pk_fma_f32 v[98:99], v[38:39], v[114:115], v[98:99] op_sel_hi:[1,0,1] neg_lo:[1,0,0] neg_hi:[1,0,0]
	v_pk_fma_f32 v[100:101], v[40:41], v[114:115], v[100:101] op_sel_hi:[1,0,1]
	v_pk_fma_f32 v[110:111], v[110:111], v[116:117], v[58:59] op_sel_hi:[1,0,1]
	v_pk_fma_f32 v[112:113], v[158:159], v[114:115], v[112:113] op_sel_hi:[1,0,1]
	v_mul_f32_e32 v65, 0xbfb8aa3b, v110
	v_exp_f32_e32 v65, v65
	v_pk_fma_f32 v[106:107], v[46:47], v[114:115], v[106:107] op_sel_hi:[1,0,1] neg_lo:[1,0,0] neg_hi:[1,0,0]
	v_pk_fma_f32 v[108:109], v[48:49], v[114:115], v[108:109] op_sel_hi:[1,0,1]
	v_pk_fma_f32 v[102:103], v[54:55], v[114:115], v[102:103] op_sel_hi:[1,0,1] neg_lo:[1,0,0] neg_hi:[1,0,0]
	v_add_f32_e32 v65, 1.0, v65
	v_pk_fma_f32 v[104:105], v[56:57], v[114:115], v[104:105] op_sel_hi:[1,0,1]
	v_pk_fma_f32 v[114:115], v[100:101], v[116:117], v[36:37] op_sel_hi:[1,0,1]
	v_pk_fma_f32 v[100:101], v[98:99], v[116:117], v[34:35] op_sel_hi:[1,0,1]
	v_rcp_f32_e32 v98, v65
	v_mul_f32_e32 v65, 0xbfb8aa3b, v111
	v_exp_f32_e32 v65, v65
	v_pk_fma_f32 v[112:113], v[112:113], v[116:117], v[60:61] op_sel_hi:[1,0,1]
	v_pk_fma_f32 v[102:103], v[102:103], v[116:117], v[50:51] op_sel_hi:[1,0,1]
	v_pk_fma_f32 v[106:107], v[106:107], v[116:117], v[42:43] op_sel_hi:[1,0,1]
	v_add_f32_e32 v65, 1.0, v65
	v_rcp_f32_e32 v99, v65
	v_mul_f32_e32 v65, 0xbfb8aa3b, v112
	v_exp_f32_e32 v65, v65
	v_pk_fma_f32 v[104:105], v[104:105], v[116:117], v[52:53] op_sel_hi:[1,0,1]
	v_pk_mul_f32 v[98:99], v[110:111], v[98:99]
	v_pk_fma_f32 v[108:109], v[108:109], v[116:117], v[44:45] op_sel_hi:[1,0,1]
	v_add_f32_e32 v65, 1.0, v65
	v_pk_mul_f32 v[98:99], v[102:103], v[98:99]
	v_rcp_f32_e32 v102, v65
	v_mul_f32_e32 v65, 0xbfb8aa3b, v113
	v_exp_f32_e32 v65, v65
	v_cvt_pk_bf16_f32 v98, v98, v99
	v_add_f32_e32 v65, 1.0, v65
	v_rcp_f32_e32 v103, v65
	v_mul_f32_e32 v65, 0xbfb8aa3b, v106
	v_exp_f32_e32 v65, v65
	v_pk_mul_f32 v[102:103], v[112:113], v[102:103]
	s_nop 0
	v_pk_mul_f32 v[102:103], v[104:105], v[102:103]
	v_add_f32_e32 v65, 1.0, v65
	v_cvt_pk_bf16_f32 v99, v102, v103
	v_rcp_f32_e32 v102, v65
	v_mul_f32_e32 v65, 0xbfb8aa3b, v107
	v_exp_f32_e32 v65, v65
	s_nop 0
	v_add_f32_e32 v65, 1.0, v65
	v_rcp_f32_e32 v103, v65
	v_mul_f32_e32 v65, 0xbfb8aa3b, v108
	v_exp_f32_e32 v65, v65
	v_pk_mul_f32 v[102:103], v[106:107], v[102:103]
	s_nop 0
	v_pk_mul_f32 v[100:101], v[100:101], v[102:103]
	v_add_f32_e32 v65, 1.0, v65
	v_rcp_f32_e32 v102, v65
	v_mul_f32_e32 v65, 0xbfb8aa3b, v109
	v_exp_f32_e32 v65, v65
	v_cvt_pk_bf16_f32 v100, v100, v101
	v_add_f32_e32 v65, 1.0, v65
	v_rcp_f32_e32 v103, v65
	v_mad_i64_i32 v[64:65], s[2:3], v64, s15, v[150:151]
	v_lshl_add_u64 v[64:65], v[64:65], 0, v[152:153]
	v_pk_mul_f32 v[102:103], v[108:109], v[102:103]
	s_nop 0
	v_pk_mul_f32 v[102:103], v[114:115], v[102:103]
	s_nop 0
	v_cvt_pk_bf16_f32 v101, v102, v103
	global_store_dwordx4 v[64:65], v[98:101], off
	v_add_u32_e32 v64, 0x80, v172
	v_ashrrev_i32_e32 v65, 31, v64
	v_lshlrev_b64 v[98:99], 7, v[64:65]
	v_lshl_add_u64 v[98:99], s[22:23], 0, v[98:99]
	v_lshl_add_u64 v[102:103], v[98:99], 0, v[174:175]
	v_add_u32_e32 v250, 0x90, v172
	v_ashrrev_i32_e32 v251, 31, v250
	v_lshlrev_b64 v[250:251], 7, v[250:251]
	v_lshl_add_u64 v[250:251], s[22:23], 0, v[250:251]
	v_lshl_add_u64 v[250:251], v[250:251], 0, v[174:175]
	global_load_dwordx4 v[224:227], v[250:251], off offset:16
	global_load_dwordx4 v[228:231], v[250:251], off
	s_nop 0
	s_nop 0
	s_waitcnt vmcnt(3)
	v_mov_b32_e32 v98, v232
	v_mov_b32_e32 v99, v233
	v_mov_b32_e32 v100, v234
	v_mov_b32_e32 v101, v235
	v_mov_b32_e32 v102, v236
	v_mov_b32_e32 v103, v237
	v_mov_b32_e32 v104, v238
	v_mov_b32_e32 v105, v239
	v_pk_add_f32 v[98:99], v[98:99], v[100:101]
	s_nop 0
	v_pk_add_f32 v[102:103], v[102:103], v[104:105]
	s_nop 0
	v_pk_add_f32 v[98:99], v[102:103], v[98:99]
	ds_bpermute_b32 v100, v183, v98
	ds_bpermute_b32 v101, v183, v99
	s_waitcnt lgkmcnt(0)
	v_pk_add_f32 v[98:99], v[98:99], v[100:101]
	ds_bpermute_b32 v100, v182, v98
	ds_bpermute_b32 v101, v182, v99
	s_waitcnt lgkmcnt(0)
; DI float bperm(float v, int srclane) { return __int_as_float(__builtin_amdgcn_ds_bpermute(srclane << 2, __float_as_int(v))); }
; DI unsigned pk2(float lo, float hi) { const f32x2 v = {lo, hi}; const hwbf16x2 b = __builtin_convertvector(v, hwbf16x2); return __builtin_bit_cast(unsigned, b); }
; DI float silu_f(float x) { return x * __builtin_amdgcn_rcpf(1.0f + __expf(-x)); }
; DI void row_stats(const float* STAT, int row, int fq, int lane, float& mu, float& rstd) {
;     const f32x4 a = *(const f32x4*)(STAT + (size_t)row * 32 + fq * 8), b = *(const f32x4*)(STAT + (size_t)row * 32 + fq * 8 + 4);
;     float s = (a[0] + a[2]) + (b[0] + b[2]), q = (a[1] + a[3]) + (b[1] + b[3]);
;     s += bperm(s, lane ^ 16); q += bperm(q, lane ^ 16); s += bperm(s, lane ^ 32); q += bperm(q, lane ^ 32);
;     mu = s * (1.0f / 1024.0f); rstd = __builtin_amdgcn_rsqf(fmaxf(q * (1.0f / 1024.0f) - mu * mu, 0.f) + EPS);
; }
;     DI void operator()(const f32x4 (&acc)[2][2][4][2], const pg8::Unit& u, int wr, int wc, int fr, int fq) const {
;     ...
;             for (int m = 0; m < 4; ++m) { const int row = row0 + ai * 128 + m * 16; float mu, rstd; row_stats(STAT, row, fq, lane, mu, rstd);
;                 const f32x4 g0 = (acc[ai][0][m][0] - c1[0][0] * mu) * rstd + c2[0][0], g1 = (acc[ai][0][m][1] - c1[0][1] * mu) * rstd + c2[0][1];
;                 const f32x4 u0 = (acc[ai][1][m][0] - c1[1][0] * mu) * rstd + c2[1][0], u1 = (acc[ai][1][m][1] - c1[1][1] * mu) * rstd + c2[1][1];
;                 u32x4 w; w.x = pk2(silu_f(g0[0]) * u0[0], silu_f(g0[1]) * u0[1]); w.y = pk2(silu_f(g0[2]) * u0[2], silu_f(g0[3]) * u0[3]);
;                 w.z = pk2(silu_f(g1[0]) * u1[0], silu_f(g1[1]) * u1[1]); w.w = pk2(silu_f(g1[2]) * u1[2], silu_f(g1[3]) * u1[3]);
;                 *(u32x4*)(HID + (size_t)row * DFF + col0) = w; }
	v_pk_add_f32 v[98:99], v[98:99], v[100:101]
	s_nop 0
	v_pk_mul_f32 v[98:99], v[98:99], s[34:35] op_sel_hi:[1,0]
	s_nop 0
	v_fma_f32 v65, -v98, v98, v99
	v_max_f32_e32 v65, 0, v65
	v_add_f32_e32 v65, 0x3727c5ac, v65
	v_rsq_f32_e32 v100, v65
	v_pk_fma_f32 v[94:95], v[62:63], v[98:99], v[94:95] op_sel_hi:[1,0,1] neg_lo:[1,0,0] neg_hi:[1,0,0]
	v_pk_fma_f32 v[82:83], v[38:39], v[98:99], v[82:83] op_sel_hi:[1,0,1] neg_lo:[1,0,0] neg_hi:[1,0,0]
	v_pk_fma_f32 v[84:85], v[40:41], v[98:99], v[84:85] op_sel_hi:[1,0,1]
	v_pk_fma_f32 v[94:95], v[94:95], v[100:101], v[58:59] op_sel_hi:[1,0,1]
	v_pk_fma_f32 v[96:97], v[158:159], v[98:99], v[96:97] op_sel_hi:[1,0,1]
	v_mul_f32_e32 v65, 0xbfb8aa3b, v94
	v_exp_f32_e32 v65, v65
	v_pk_fma_f32 v[90:91], v[46:47], v[98:99], v[90:91] op_sel_hi:[1,0,1] neg_lo:[1,0,0] neg_hi:[1,0,0]
	v_pk_fma_f32 v[92:93], v[48:49], v[98:99], v[92:93] op_sel_hi:[1,0,1]
	v_pk_fma_f32 v[86:87], v[54:55], v[98:99], v[86:87] op_sel_hi:[1,0,1] neg_lo:[1,0,0] neg_hi:[1,0,0]
	v_add_f32_e32 v65, 1.0, v65
	v_pk_fma_f32 v[88:89], v[56:57], v[98:99], v[88:89] op_sel_hi:[1,0,1]
	v_pk_fma_f32 v[98:99], v[84:85], v[100:101], v[36:37] op_sel_hi:[1,0,1]
	v_pk_fma_f32 v[84:85], v[82:83], v[100:101], v[34:35] op_sel_hi:[1,0,1]
	v_rcp_f32_e32 v82, v65
	v_mul_f32_e32 v65, 0xbfb8aa3b, v95
	v_exp_f32_e32 v65, v65
	v_pk_fma_f32 v[96:97], v[96:97], v[100:101], v[60:61] op_sel_hi:[1,0,1]
	v_pk_fma_f32 v[86:87], v[86:87], v[100:101], v[50:51] op_sel_hi:[1,0,1]
	v_pk_fma_f32 v[90:91], v[90:91], v[100:101], v[42:43] op_sel_hi:[1,0,1]
	v_add_f32_e32 v65, 1.0, v65
	v_rcp_f32_e32 v83, v65
	v_mul_f32_e32 v65, 0xbfb8aa3b, v96
	v_exp_f32_e32 v65, v65
	v_pk_fma_f32 v[88:89], v[88:89], v[100:101], v[52:53] op_sel_hi:[1,0,1]
	v_pk_mul_f32 v[82:83], v[94:95], v[82:83]
	v_pk_fma_f32 v[92:93], v[92:93], v[100:101], v[44:45] op_sel_hi:[1,0,1]
	v_add_f32_e32 v65, 1.0, v65
	v_pk_mul_f32 v[82:83], v[86:87], v[82:83]
	v_rcp_f32_e32 v86, v65
	v_mul_f32_e32 v65, 0xbfb8aa3b, v97
	v_exp_f32_e32 v65, v65
	v_cvt_pk_bf16_f32 v82, v82, v83
	v_add_f32_e32 v65, 1.0, v65
	v_rcp_f32_e32 v87, v65
	v_mul_f32_e32 v65, 0xbfb8aa3b, v90
	v_exp_f32_e32 v65, v65
	v_pk_mul_f32 v[86:87], v[96:97], v[86:87]
	s_nop 0
	v_pk_mul_f32 v[86:87], v[88:89], v[86:87]
	v_add_f32_e32 v65, 1.0, v65
	v_cvt_pk_bf16_f32 v83, v86, v87
	v_rcp_f32_e32 v86, v65
	v_mul_f32_e32 v65, 0xbfb8aa3b, v91
	v_exp_f32_e32 v65, v65
	s_nop 0
	v_add_f32_e32 v65, 1.0, v65
	v_rcp_f32_e32 v87, v65
	v_mul_f32_e32 v65, 0xbfb8aa3b, v92
	v_exp_f32_e32 v65, v65
	v_pk_mul_f32 v[86:87], v[90:91], v[86:87]
	s_nop 0
	v_pk_mul_f32 v[84:85], v[84:85], v[86:87]
	v_add_f32_e32 v65, 1.0, v65
	v_rcp_f32_e32 v86, v65
	v_mul_f32_e32 v65, 0xbfb8aa3b, v93
	v_exp_f32_e32 v65, v65
	v_cvt_pk_bf16_f32 v84, v84, v85
	v_add_f32_e32 v65, 1.0, v65
	v_rcp_f32_e32 v87, v65
	v_mad_i64_i32 v[64:65], s[2:3], v64, s15, v[150:151]
	v_lshl_add_u64 v[64:65], v[64:65], 0, v[152:153]
	v_pk_mul_f32 v[86:87], v[92:93], v[86:87]
	s_nop 0
	v_pk_mul_f32 v[86:87], v[98:99], v[86:87]
	s_nop 0
	v_cvt_pk_bf16_f32 v85, v86, v87
	global_store_dwordx4 v[64:65], v[82:85], off
	v_add_u32_e32 v64, 0x90, v172
	v_ashrrev_i32_e32 v65, 31, v64
	v_lshlrev_b64 v[82:83], 7, v[64:65]
	v_lshl_add_u64 v[82:83], s[22:23], 0, v[82:83]
	v_lshl_add_u64 v[86:87], v[82:83], 0, v[174:175]
	v_add_u32_e32 v250, 0xa0, v172
	v_ashrrev_i32_e32 v251, 31, v250
	v_lshlrev_b64 v[250:251], 7, v[250:251]
	v_lshl_add_u64 v[250:251], s[22:23], 0, v[250:251]
	v_lshl_add_u64 v[250:251], v[250:251], 0, v[174:175]
	global_load_dwordx4 v[232:235], v[250:251], off offset:16
	global_load_dwordx4 v[236:239], v[250:251], off
	s_nop 0
	s_nop 0
	s_waitcnt vmcnt(3)
	v_mov_b32_e32 v82, v224
	v_mov_b32_e32 v83, v225
	v_mov_b32_e32 v84, v226
	v_mov_b32_e32 v85, v227
	v_mov_b32_e32 v86, v228
	v_mov_b32_e32 v87, v229
	v_mov_b32_e32 v88, v230
	v_mov_b32_e32 v89, v231
	v_pk_add_f32 v[82:83], v[82:83], v[84:85]
	s_nop 0
	v_pk_add_f32 v[86:87], v[86:87], v[88:89]
	s_nop 0
	v_pk_add_f32 v[82:83], v[86:87], v[82:83]
	ds_bpermute_b32 v84, v183, v82
	ds_bpermute_b32 v85, v183, v83
	s_waitcnt lgkmcnt(0)
	v_pk_add_f32 v[82:83], v[82:83], v[84:85]
	ds_bpermute_b32 v84, v182, v82
	ds_bpermute_b32 v85, v182, v83
	s_waitcnt lgkmcnt(0)
	v_pk_add_f32 v[82:83], v[82:83], v[84:85]
	s_nop 0
	v_pk_mul_f32 v[82:83], v[82:83], s[34:35] op_sel_hi:[1,0]
	s_nop 0
	v_fma_f32 v65, -v82, v82, v83
	v_max_f32_e32 v65, 0, v65
	v_add_f32_e32 v65, 0x3727c5ac, v65
	v_rsq_f32_e32 v84, v65
	v_pk_fma_f32 v[78:79], v[62:63], v[82:83], v[78:79] op_sel_hi:[1,0,1] neg_lo:[1,0,0] neg_hi:[1,0,0]
	v_pk_fma_f32 v[66:67], v[38:39], v[82:83], v[66:67] op_sel_hi:[1,0,1] neg_lo:[1,0,0] neg_hi:[1,0,0]
	v_pk_fma_f32 v[68:69], v[40:41], v[82:83], v[68:69] op_sel_hi:[1,0,1]
	v_pk_fma_f32 v[78:79], v[78:79], v[84:85], v[58:59] op_sel_hi:[1,0,1]
	v_pk_fma_f32 v[80:81], v[158:159], v[82:83], v[80:81] op_sel_hi:[1,0,1]
	v_mul_f32_e32 v65, 0xbfb8aa3b, v78
	v_exp_f32_e32 v65, v65
	v_pk_fma_f32 v[74:75], v[46:47], v[82:83], v[74:75] op_sel_hi:[1,0,1] neg_lo:[1,0,0] neg_hi:[1,0,0]
	v_pk_fma_f32 v[76:77], v[48:49], v[82:83], v[76:77] op_sel_hi:[1,0,1]
	v_pk_fma_f32 v[70:71], v[54:55], v[82:83], v[70:71] op_sel_hi:[1,0,1] neg_lo:[1,0,0] neg_hi:[1,0,0]
	v_add_f32_e32 v65, 1.0, v65
	v_pk_fma_f32 v[72:73], v[56:57], v[82:83], v[72:73] op_sel_hi:[1,0,1]
	v_pk_fma_f32 v[82:83], v[68:69], v[84:85], v[36:37] op_sel_hi:[1,0,1]
	v_pk_fma_f32 v[68:69], v[66:67], v[84:85], v[34:35] op_sel_hi:[1,0,1]
	v_rcp_f32_e32 v66, v65
	v_mul_f32_e32 v65, 0xbfb8aa3b, v79
	v_exp_f32_e32 v65, v65
	v_pk_fma_f32 v[80:81], v[80:81], v[84:85], v[60:61] op_sel_hi:[1,0,1]
	v_pk_fma_f32 v[70:71], v[70:71], v[84:85], v[50:51] op_sel_hi:[1,0,1]
; DI float bperm(float v, int srclane) { return __int_as_float(__builtin_amdgcn_ds_bpermute(srclane << 2, __float_as_int(v))); }
; DI unsigned pk2(float lo, float hi) { const f32x2 v = {lo, hi}; const hwbf16x2 b = __builtin_convertvector(v, hwbf16x2); return __builtin_bit_cast(unsigned, b); }
; DI float silu_f(float x) { return x * __builtin_amdgcn_rcpf(1.0f + __expf(-x)); }
; DI void row_stats(const float* STAT, int row, int fq, int lane, float& mu, float& rstd) {
;     const f32x4 a = *(const f32x4*)(STAT + (size_t)row * 32 + fq * 8), b = *(const f32x4*)(STAT + (size_t)row * 32 + fq * 8 + 4);
;     float s = (a[0] + a[2]) + (b[0] + b[2]), q = (a[1] + a[3]) + (b[1] + b[3]);
;     s += bperm(s, lane ^ 16); q += bperm(q, lane ^ 16); s += bperm(s, lane ^ 32); q += bperm(q, lane ^ 32);
;     mu = s * (1.0f / 1024.0f); rstd = __builtin_amdgcn_rsqf(fmaxf(q * (1.0f / 1024.0f) - mu * mu, 0.f) + EPS);
; }
;     DI void operator()(const f32x4 (&acc)[2][2][4][2], const pg8::Unit& u, int wr, int wc, int fr, int fq) const {
;     ...
;             for (int m = 0; m < 4; ++m) { const int row = row0 + ai * 128 + m * 16; float mu, rstd; row_stats(STAT, row, fq, lane, mu, rstd);
;                 const f32x4 g0 = (acc[ai][0][m][0] - c1[0][0] * mu) * rstd + c2[0][0], g1 = (acc[ai][0][m][1] - c1[0][1] * mu) * rstd + c2[0][1];
;                 const f32x4 u0 = (acc[ai][1][m][0] - c1[1][0] * mu) * rstd + c2[1][0], u1 = (acc[ai][1][m][1] - c1[1][1] * mu) * rstd + c2[1][1];
;                 u32x4 w; w.x = pk2(silu_f(g0[0]) * u0[0], silu_f(g0[1]) * u0[1]); w.y = pk2(silu_f(g0[2]) * u0[2], silu_f(g0[3]) * u0[3]);
;                 w.z = pk2(silu_f(g1[0]) * u1[0], silu_f(g1[1]) * u1[1]); w.w = pk2(silu_f(g1[2]) * u1[2], silu_f(g1[3]) * u1[3]);
;                 *(u32x4*)(HID + (size_t)row * DFF + col0) = w; }
	v_pk_fma_f32 v[74:75], v[74:75], v[84:85], v[42:43] op_sel_hi:[1,0,1]
	v_add_f32_e32 v65, 1.0, v65
	v_rcp_f32_e32 v67, v65
	v_mul_f32_e32 v65, 0xbfb8aa3b, v80
	v_exp_f32_e32 v65, v65
	v_pk_fma_f32 v[72:73], v[72:73], v[84:85], v[52:53] op_sel_hi:[1,0,1]
	v_pk_mul_f32 v[66:67], v[78:79], v[66:67]
	v_pk_fma_f32 v[76:77], v[76:77], v[84:85], v[44:45] op_sel_hi:[1,0,1]
	v_add_f32_e32 v65, 1.0, v65
	v_pk_mul_f32 v[66:67], v[70:71], v[66:67]
	v_rcp_f32_e32 v70, v65
	v_mul_f32_e32 v65, 0xbfb8aa3b, v81
	v_exp_f32_e32 v65, v65
	v_cvt_pk_bf16_f32 v66, v66, v67
	v_add_f32_e32 v65, 1.0, v65
	v_rcp_f32_e32 v71, v65
	v_mul_f32_e32 v65, 0xbfb8aa3b, v74
	v_exp_f32_e32 v65, v65
	v_pk_mul_f32 v[70:71], v[80:81], v[70:71]
	s_nop 0
	v_pk_mul_f32 v[70:71], v[72:73], v[70:71]
	v_add_f32_e32 v65, 1.0, v65
	v_cvt_pk_bf16_f32 v67, v70, v71
	v_rcp_f32_e32 v70, v65
	v_mul_f32_e32 v65, 0xbfb8aa3b, v75
	v_exp_f32_e32 v65, v65
	s_nop 0
	v_add_f32_e32 v65, 1.0, v65
	v_rcp_f32_e32 v71, v65
	v_mul_f32_e32 v65, 0xbfb8aa3b, v76
	v_exp_f32_e32 v65, v65
	v_pk_mul_f32 v[70:71], v[74:75], v[70:71]
	s_nop 0
	v_pk_mul_f32 v[68:69], v[68:69], v[70:71]
	v_add_f32_e32 v65, 1.0, v65
	v_rcp_f32_e32 v70, v65
	v_mul_f32_e32 v65, 0xbfb8aa3b, v77
	v_exp_f32_e32 v65, v65
	v_cvt_pk_bf16_f32 v68, v68, v69
	v_add_f32_e32 v65, 1.0, v65
	v_rcp_f32_e32 v71, v65
	v_mad_i64_i32 v[64:65], s[2:3], v64, s15, v[150:151]
	v_lshl_add_u64 v[64:65], v[64:65], 0, v[152:153]
	v_pk_mul_f32 v[70:71], v[76:77], v[70:71]
	s_nop 0
	v_pk_mul_f32 v[70:71], v[82:83], v[70:71]
	s_nop 0
	v_cvt_pk_bf16_f32 v69, v70, v71
	global_store_dwordx4 v[64:65], v[66:69], off
	s_nop 1
	v_add_u32_e32 v68, 0xa0, v172
	v_ashrrev_i32_e32 v69, 31, v68
	v_lshlrev_b64 v[64:65], 7, v[68:69]
	v_lshl_add_u64 v[64:65], s[22:23], 0, v[64:65]
	v_lshl_add_u64 v[70:71], v[64:65], 0, v[174:175]
	v_add_u32_e32 v250, 0xb0, v172
	v_ashrrev_i32_e32 v251, 31, v250
	v_lshlrev_b64 v[250:251], 7, v[250:251]
	v_lshl_add_u64 v[250:251], s[22:23], 0, v[250:251]
	v_lshl_add_u64 v[250:251], v[250:251], 0, v[174:175]
	global_load_dwordx4 v[224:227], v[250:251], off offset:16
	global_load_dwordx4 v[228:231], v[250:251], off
	s_nop 0
	s_nop 0
	s_waitcnt vmcnt(3)
	v_mov_b32_e32 v64, v232
	v_mov_b32_e32 v65, v233
	v_mov_b32_e32 v66, v234
	v_mov_b32_e32 v67, v235
	v_mov_b32_e32 v70, v236
	v_mov_b32_e32 v71, v237
	v_mov_b32_e32 v72, v238
	v_mov_b32_e32 v73, v239
	v_pk_add_f32 v[64:65], v[64:65], v[66:67]
	s_nop 0
	v_pk_add_f32 v[70:71], v[70:71], v[72:73]
	s_nop 0
	v_pk_add_f32 v[64:65], v[70:71], v[64:65]
	ds_bpermute_b32 v66, v183, v64
	ds_bpermute_b32 v67, v183, v65
	s_waitcnt lgkmcnt(0)
	v_pk_add_f32 v[64:65], v[64:65], v[66:67]
	ds_bpermute_b32 v66, v182, v64
	ds_bpermute_b32 v67, v182, v65
	s_waitcnt lgkmcnt(0)
	v_pk_add_f32 v[64:65], v[64:65], v[66:67]
	s_nop 0
	v_pk_mul_f32 v[64:65], v[64:65], s[34:35] op_sel_hi:[1,0]
	s_nop 0
	v_fma_f32 v66, -v64, v64, v65
	v_max_f32_e32 v66, 0, v66
	v_add_f32_e32 v66, 0x3727c5ac, v66
	v_rsq_f32_e32 v66, v66
	v_pk_fma_f32 v[30:31], v[62:63], v[64:65], v[30:31] op_sel_hi:[1,0,1] neg_lo:[1,0,0] neg_hi:[1,0,0]
	v_pk_fma_f32 v[18:19], v[38:39], v[64:65], v[18:19] op_sel_hi:[1,0,1] neg_lo:[1,0,0] neg_hi:[1,0,0]
	v_pk_fma_f32 v[20:21], v[40:41], v[64:65], v[20:21] op_sel_hi:[1,0,1]
	v_pk_fma_f32 v[30:31], v[30:31], v[66:67], v[58:59] op_sel_hi:[1,0,1]
	v_pk_fma_f32 v[32:33], v[158:159], v[64:65], v[32:33] op_sel_hi:[1,0,1]
	v_pk_fma_f32 v[26:27], v[46:47], v[64:65], v[26:27] op_sel_hi:[1,0,1] neg_lo:[1,0,0] neg_hi:[1,0,0]
	v_pk_fma_f32 v[28:29], v[48:49], v[64:65], v[28:29] op_sel_hi:[1,0,1]
	v_pk_fma_f32 v[22:23], v[54:55], v[64:65], v[22:23] op_sel_hi:[1,0,1] neg_lo:[1,0,0] neg_hi:[1,0,0]
	v_pk_fma_f32 v[24:25], v[56:57], v[64:65], v[24:25] op_sel_hi:[1,0,1]
	v_pk_fma_f32 v[64:65], v[20:21], v[66:67], v[36:37] op_sel_hi:[1,0,1]
	v_pk_fma_f32 v[20:21], v[18:19], v[66:67], v[34:35] op_sel_hi:[1,0,1]
	v_mul_f32_e32 v18, 0xbfb8aa3b, v30
	v_mul_f32_e32 v19, 0xbfb8aa3b, v31
	v_exp_f32_e32 v18, v18
	v_exp_f32_e32 v19, v19
	v_pk_fma_f32 v[22:23], v[22:23], v[66:67], v[50:51] op_sel_hi:[1,0,1]
	v_pk_fma_f32 v[32:33], v[32:33], v[66:67], v[60:61] op_sel_hi:[1,0,1]
	v_add_f32_e32 v18, 1.0, v18
	v_add_f32_e32 v19, 1.0, v19
	v_rcp_f32_e32 v18, v18
	v_rcp_f32_e32 v19, v19
	v_pk_fma_f32 v[24:25], v[24:25], v[66:67], v[52:53] op_sel_hi:[1,0,1]
	v_pk_fma_f32 v[26:27], v[26:27], v[66:67], v[42:43] op_sel_hi:[1,0,1]
	v_pk_fma_f32 v[28:29], v[28:29], v[66:67], v[44:45] op_sel_hi:[1,0,1]
	v_pk_mul_f32 v[18:19], v[30:31], v[18:19]
	s_nop 0
	v_pk_mul_f32 v[18:19], v[22:23], v[18:19]
	s_nop 0
	v_cvt_pk_bf16_f32 v18, v18, v19
	v_mul_f32_e32 v19, 0xbfb8aa3b, v32
	v_exp_f32_e32 v19, v19
	s_nop 0
	v_add_f32_e32 v19, 1.0, v19
	v_rcp_f32_e32 v22, v19
	v_mul_f32_e32 v19, 0xbfb8aa3b, v33
	v_exp_f32_e32 v19, v19
	s_nop 0
	v_add_f32_e32 v19, 1.0, v19
	v_rcp_f32_e32 v23, v19
	s_nop 0
	v_pk_mul_f32 v[22:23], v[32:33], v[22:23]
	s_nop 0
	v_pk_mul_f32 v[22:23], v[24:25], v[22:23]
	s_nop 0
	v_cvt_pk_bf16_f32 v19, v22, v23
	v_mul_f32_e32 v22, 0xbfb8aa3b, v26
	v_mul_f32_e32 v23, 0xbfb8aa3b, v27
	v_exp_f32_e32 v22, v22
	v_exp_f32_e32 v23, v23
	v_add_f32_e32 v22, 1.0, v22
	v_add_f32_e32 v23, 1.0, v23
	v_rcp_f32_e32 v22, v22
	v_rcp_f32_e32 v23, v23
	s_nop 0
	v_pk_mul_f32 v[22:23], v[26:27], v[22:23]
	s_nop 0
	v_pk_mul_f32 v[20:21], v[20:21], v[22:23]
	s_nop 0
	v_cvt_pk_bf16_f32 v20, v20, v21
	v_mul_f32_e32 v21, 0xbfb8aa3b, v28
	v_exp_f32_e32 v21, v21
	s_nop 0
	v_add_f32_e32 v21, 1.0, v21
	v_rcp_f32_e32 v22, v21
	v_mul_f32_e32 v21, 0xbfb8aa3b, v29
	v_exp_f32_e32 v21, v21
	s_nop 0
	v_add_f32_e32 v21, 1.0, v21
	v_rcp_f32_e32 v23, v21
	s_nop 0
	v_pk_mul_f32 v[22:23], v[28:29], v[22:23]
	s_nop 0
	v_pk_mul_f32 v[22:23], v[64:65], v[22:23]
	s_nop 0
	v_cvt_pk_bf16_f32 v21, v22, v23
	v_mad_i64_i32 v[22:23], s[2:3], v68, s15, v[150:151]
	v_lshl_add_u64 v[22:23], v[22:23], 0, v[152:153]
	global_store_dwordx4 v[22:23], v[18:21], off
	v_add_u32_e32 v22, 0xb0, v172
	v_ashrrev_i32_e32 v23, 31, v22
	v_lshlrev_b64 v[18:19], 7, v[22:23]
	v_lshl_add_u64 v[18:19], s[22:23], 0, v[18:19]
	v_lshl_add_u64 v[24:25], v[18:19], 0, v[174:175]
	s_nop 0
	s_nop 0
	s_nop 0
	s_waitcnt vmcnt(1)
; DI float bperm(float v, int srclane) { return __int_as_float(__builtin_amdgcn_ds_bpermute(srclane << 2, __float_as_int(v))); }
; DI unsigned pk2(float lo, float hi) { const f32x2 v = {lo, hi}; const hwbf16x2 b = __builtin_convertvector(v, hwbf16x2); return __builtin_bit_cast(unsigned, b); }
; DI float silu_f(float x) { return x * __builtin_amdgcn_rcpf(1.0f + __expf(-x)); }
; DI void row_stats(const float* STAT, int row, int fq, int lane, float& mu, float& rstd) {
;     const f32x4 a = *(const f32x4*)(STAT + (size_t)row * 32 + fq * 8), b = *(const f32x4*)(STAT + (size_t)row * 32 + fq * 8 + 4);
;     float s = (a[0] + a[2]) + (b[0] + b[2]), q = (a[1] + a[3]) + (b[1] + b[3]);
;     s += bperm(s, lane ^ 16); q += bperm(q, lane ^ 16); s += bperm(s, lane ^ 32); q += bperm(q, lane ^ 32);
;     mu = s * (1.0f / 1024.0f); rstd = __builtin_amdgcn_rsqf(fmaxf(q * (1.0f / 1024.0f) - mu * mu, 0.f) + EPS);
; }
;     DI void operator()(const f32x4 (&acc)[2][2][4][2], const pg8::Unit& u, int wr, int wc, int fr, int fq) const {
;     ...
;             for (int m = 0; m < 4; ++m) { const int row = row0 + ai * 128 + m * 16; float mu, rstd; row_stats(STAT, row, fq, lane, mu, rstd);
;                 const f32x4 g0 = (acc[ai][0][m][0] - c1[0][0] * mu) * rstd + c2[0][0], g1 = (acc[ai][0][m][1] - c1[0][1] * mu) * rstd + c2[0][1];
;                 const f32x4 u0 = (acc[ai][1][m][0] - c1[1][0] * mu) * rstd + c2[1][0], u1 = (acc[ai][1][m][1] - c1[1][1] * mu) * rstd + c2[1][1];
;                 u32x4 w; w.x = pk2(silu_f(g0[0]) * u0[0], silu_f(g0[1]) * u0[1]); w.y = pk2(silu_f(g0[2]) * u0[2], silu_f(g0[3]) * u0[3]);
;                 w.z = pk2(silu_f(g1[0]) * u1[0], silu_f(g1[1]) * u1[1]); w.w = pk2(silu_f(g1[2]) * u1[2], silu_f(g1[3]) * u1[3]);
;                 *(u32x4*)(HID + (size_t)row * DFF + col0) = w; }
	v_mov_b32_e32 v18, v224
	v_mov_b32_e32 v19, v225
	v_mov_b32_e32 v20, v226
	v_mov_b32_e32 v21, v227
	v_mov_b32_e32 v24, v228
	v_mov_b32_e32 v25, v229
	v_mov_b32_e32 v26, v230
	v_mov_b32_e32 v27, v231
	v_pk_add_f32 v[18:19], v[18:19], v[20:21]
	s_nop 0
	v_pk_add_f32 v[24:25], v[24:25], v[26:27]
	s_nop 0
	v_pk_add_f32 v[18:19], v[24:25], v[18:19]
	ds_bpermute_b32 v20, v183, v18
	ds_bpermute_b32 v21, v183, v19
	s_waitcnt lgkmcnt(0)
	v_pk_add_f32 v[18:19], v[18:19], v[20:21]
	ds_bpermute_b32 v20, v182, v18
	ds_bpermute_b32 v21, v182, v19
	s_waitcnt lgkmcnt(0)
	v_pk_add_f32 v[18:19], v[18:19], v[20:21]
	s_nop 0
	v_pk_mul_f32 v[18:19], v[18:19], s[34:35] op_sel_hi:[1,0]
	s_nop 0
	v_fma_f32 v20, -v18, v18, v19
	v_max_f32_e32 v20, 0, v20
	v_add_f32_e32 v20, 0x3727c5ac, v20
	v_rsq_f32_e32 v20, v20
	v_pk_fma_f32 v[14:15], v[62:63], v[18:19], v[14:15] op_sel_hi:[1,0,1] neg_lo:[1,0,0] neg_hi:[1,0,0]
	v_pk_fma_f32 v[2:3], v[38:39], v[18:19], v[2:3] op_sel_hi:[1,0,1] neg_lo:[1,0,0] neg_hi:[1,0,0]
	v_pk_fma_f32 v[4:5], v[40:41], v[18:19], v[4:5] op_sel_hi:[1,0,1]
	v_pk_fma_f32 v[14:15], v[14:15], v[20:21], v[58:59] op_sel_hi:[1,0,1]
	v_pk_fma_f32 v[16:17], v[158:159], v[18:19], v[16:17] op_sel_hi:[1,0,1]
	v_pk_fma_f32 v[10:11], v[46:47], v[18:19], v[10:11] op_sel_hi:[1,0,1] neg_lo:[1,0,0] neg_hi:[1,0,0]
	v_pk_fma_f32 v[12:13], v[48:49], v[18:19], v[12:13] op_sel_hi:[1,0,1]
	v_pk_fma_f32 v[6:7], v[54:55], v[18:19], v[6:7] op_sel_hi:[1,0,1] neg_lo:[1,0,0] neg_hi:[1,0,0]
	v_pk_fma_f32 v[8:9], v[56:57], v[18:19], v[8:9] op_sel_hi:[1,0,1]
	v_pk_fma_f32 v[18:19], v[4:5], v[20:21], v[36:37] op_sel_hi:[1,0,1]
	v_pk_fma_f32 v[4:5], v[2:3], v[20:21], v[34:35] op_sel_hi:[1,0,1]
	v_mul_f32_e32 v2, 0xbfb8aa3b, v14
	v_mul_f32_e32 v3, 0xbfb8aa3b, v15
	v_exp_f32_e32 v2, v2
	v_exp_f32_e32 v3, v3
	v_pk_fma_f32 v[6:7], v[6:7], v[20:21], v[50:51] op_sel_hi:[1,0,1]
	v_pk_fma_f32 v[16:17], v[16:17], v[20:21], v[60:61] op_sel_hi:[1,0,1]
	v_add_f32_e32 v2, 1.0, v2
	v_add_f32_e32 v3, 1.0, v3
	v_rcp_f32_e32 v2, v2
	v_rcp_f32_e32 v3, v3
	v_pk_fma_f32 v[8:9], v[8:9], v[20:21], v[52:53] op_sel_hi:[1,0,1]
	v_pk_fma_f32 v[10:11], v[10:11], v[20:21], v[42:43] op_sel_hi:[1,0,1]
	v_pk_fma_f32 v[12:13], v[12:13], v[20:21], v[44:45] op_sel_hi:[1,0,1]
	v_pk_mul_f32 v[2:3], v[14:15], v[2:3]
	s_nop 0
	v_pk_mul_f32 v[2:3], v[6:7], v[2:3]
	s_nop 0
	v_cvt_pk_bf16_f32 v2, v2, v3
	v_mul_f32_e32 v3, 0xbfb8aa3b, v16
	v_exp_f32_e32 v3, v3
	s_nop 0
	v_add_f32_e32 v3, 1.0, v3
	v_rcp_f32_e32 v6, v3
	v_mul_f32_e32 v3, 0xbfb8aa3b, v17
	v_exp_f32_e32 v3, v3
	s_nop 0
	v_add_f32_e32 v3, 1.0, v3
	v_rcp_f32_e32 v7, v3
	s_nop 0
	v_pk_mul_f32 v[6:7], v[16:17], v[6:7]
	s_nop 0
	v_pk_mul_f32 v[6:7], v[8:9], v[6:7]
	s_nop 0
	v_cvt_pk_bf16_f32 v3, v6, v7
	v_mul_f32_e32 v6, 0xbfb8aa3b, v10
	v_mul_f32_e32 v7, 0xbfb8aa3b, v11
	v_exp_f32_e32 v6, v6
	v_exp_f32_e32 v7, v7
	v_add_f32_e32 v6, 1.0, v6
	v_add_f32_e32 v7, 1.0, v7
	v_rcp_f32_e32 v6, v6
	v_rcp_f32_e32 v7, v7
	s_nop 0
	v_pk_mul_f32 v[6:7], v[10:11], v[6:7]
	s_nop 0
	v_pk_mul_f32 v[4:5], v[4:5], v[6:7]
	s_nop 0
	v_cvt_pk_bf16_f32 v4, v4, v5
	v_mul_f32_e32 v5, 0xbfb8aa3b, v12
	v_exp_f32_e32 v5, v5
	s_nop 0
	v_add_f32_e32 v5, 1.0, v5
	v_rcp_f32_e32 v6, v5
	v_mul_f32_e32 v5, 0xbfb8aa3b, v13
	v_exp_f32_e32 v5, v5
	s_nop 0
	v_add_f32_e32 v5, 1.0, v5
	v_rcp_f32_e32 v7, v5
	s_nop 0
	v_pk_mul_f32 v[6:7], v[12:13], v[6:7]
	s_nop 0
	v_pk_mul_f32 v[6:7], v[18:19], v[6:7]
	s_nop 0
	v_cvt_pk_bf16_f32 v5, v6, v7
	v_mad_i64_i32 v[6:7], s[2:3], v22, s15, v[150:151]
	v_lshl_add_u64 v[6:7], v[6:7], 0, v[152:153]
	s_mov_b64 s[2:3], -1
	global_store_dwordx4 v[6:7], v[2:5], off
	s_cbranch_vccnz .LBB0_1889
	s_andn2_b64 vcc, exec, s[18:19]
	s_cbranch_vccnz .LBB0_1888
	s_barrier
	s_branch .LBB0_1888
